# v27 plus last pre-barrier PV MFMA moved below the tile barrier in the MLA loop
# speedup vs baseline: 1.0134x; 1.0012x over previous
.LBB0_927:
	s_add_i32 s6, s61, -1
	s_and_b32 s77, s61, 2
	s_and_b32 s79, s6, 3
	s_cmp_eq_u32 s61, 0
	s_cselect_b64 s[8:9], -1, 0
	s_mulk_i32 s79, 0x5800
	s_and_b64 s[6:7], s[8:9], exec
	s_mul_i32 s78, s77, 0x5800
	s_cselect_b32 s6, 0, s79
	s_add_i32 s76, s78, 0
	v_add_u32_e32 v199, s76, v241
	v_add_u32_e32 v210, s6, v244
	v_exp_f32_e32 v64, v64
	v_exp_f32_e32 v65, v65
	s_nop 0
	v_add_f32_e32 v84, v65, v64
	v_cvt_pk_bf16_f32 v178, v64, v65
	v_exp_f32_e32 v64, v66
	ds_read_b128 v[182:185], v199 offset:96
	ds_read_b128 v[246:249], v199 offset:128
	ds_read_b128 v[250:253], v199 offset:160
	v_exp_f32_e32 v65, v67
	v_add_f32_e32 v66, v64, v84
	s_waitcnt lgkmcnt(4)
	v_mfma_f32_32x32x16_bf16 v[80:95], v[80:83], v[122:125], 0
	v_add_f32_e32 v66, v65, v66
	v_cvt_pk_bf16_f32 v179, v64, v65
	v_mfma_f32_32x32x16_bf16 v[80:95], v[174:177], v[126:129], v[80:95]
	v_exp_f32_e32 v64, v68
	v_exp_f32_e32 v65, v69
	v_add_f32_e32 v66, v64, v66
	v_add_f32_e32 v66, v65, v66
	v_cvt_pk_bf16_f32 v180, v64, v65
	s_waitcnt lgkmcnt(3)
	v_mfma_f32_32x32x16_bf16 v[80:95], v[170:173], v[130:133], v[80:95]
	v_exp_f32_e32 v64, v70
	v_exp_f32_e32 v65, v71
	v_add_f32_e32 v66, v64, v66
	v_add_f32_e32 v170, v65, v66
	v_cvt_pk_bf16_f32 v181, v64, v65
	s_waitcnt lgkmcnt(0)
	v_mfma_f32_32x32x16_bf16 v[80:95], v[182:185], v[134:137], v[80:95]
	ds_read_b128 v[64:67], v210 offset:13376
	ds_read_b128 v[68:71], v210 offset:13408
	ds_read_b128 v[174:177], v210 offset:17984
	ds_read_b128 v[218:221], v210 offset:18016
	v_exp_f32_e32 v72, v72
	v_exp_f32_e32 v73, v73
	v_add_f32_e32 v170, v72, v170
	v_add_f32_e32 v171, v73, v170
	v_cvt_pk_bf16_f32 v170, v72, v73
	v_mfma_f32_32x32x16_bf16 v[80:95], v[246:249], v[154:157], v[80:95]
	v_exp_f32_e32 v72, v74
	v_exp_f32_e32 v73, v75
	v_add_f32_e32 v74, v72, v171
	v_add_f32_e32 v74, v73, v74
	v_cvt_pk_bf16_f32 v171, v72, v73
	v_mfma_f32_32x32x16_bf16 v[80:95], v[250:253], v[158:161], v[80:95]
	v_exp_f32_e32 v72, v76
	v_exp_f32_e32 v73, v77
	v_add_f32_e32 v74, v72, v74
	v_add_f32_e32 v74, v73, v74
	v_cvt_pk_bf16_f32 v172, v72, v73
	s_waitcnt lgkmcnt(0)
	v_mfma_f32_32x32x16_bf16 v[16:31], v[64:67], v[162:165], v[16:31]
	v_exp_f32_e32 v64, v78
	v_exp_f32_e32 v65, v79
	v_add_f32_e32 v66, v64, v74
	v_add_f32_e32 v246, v65, v66
	v_cvt_pk_bf16_f32 v173, v64, v65
	v_mfma_f32_32x32x16_bf16 v[0:15], v[174:177], v[162:165], v[0:15]
	ds_read_b128 v[64:67], v199 offset:6656
	ds_read_b128 v[182:185], v199 offset:6688
	ds_read_b128 v[174:177], v199 offset:6720
	v_cmp_ge_f32_e32 vcc, s48, v246
	s_mov_b64 s[10:11], -1
	s_mov_b64 s[6:7], -1
	v_mfma_f32_32x32x16_bf16 v[16:31], v[68:71], v[166:169], v[16:31]
	v_exp_f32_e32 v68, v80
	v_exp_f32_e32 v69, v81
	s_nop 0
	v_add_f32_e32 v70, v69, v68
	v_cvt_pk_bf16_f32 v162, v68, v69
	v_exp_f32_e32 v80, v82
	v_exp_f32_e32 v81, v83
	v_add_f32_e32 v82, v80, v70
	v_mfma_f32_32x32x16_bf16 v[0:15], v[218:221], v[166:169], v[0:15]
	s_and_saveexec_b64 s[12:13], vcc
	v_cmp_gt_f32_e32 vcc, s49, v246
	s_and_b64 s[6:7], s[8:9], vcc
	s_orn2_b64 s[6:7], s[6:7], exec
	s_or_b64 exec, exec, s[12:13]
	v_add_u32_e32 v211, s76, v243
	ds_read_b128 v[166:169], v199 offset:6752
	ds_read_b128 v[218:221], v199 offset:6784
	ds_read_b128 v[248:251], v199 offset:6816
	s_waitcnt lgkmcnt(3)
	v_mfma_f32_32x32x16_bf16 v[64:79], v[64:67], v[98:101], 0
	v_add_f32_e32 v82, v81, v82
	v_cvt_pk_bf16_f32 v163, v80, v81
	v_mfma_f32_32x32x16_bf16 v[64:79], v[182:185], v[102:105], v[64:79]
	v_exp_f32_e32 v80, v84
	v_exp_f32_e32 v81, v85
	v_add_f32_e32 v82, v80, v82
	v_add_f32_e32 v82, v81, v82
	v_cvt_pk_bf16_f32 v164, v80, v81
	v_mfma_f32_32x32x16_bf16 v[64:79], v[174:177], v[106:109], v[64:79]
	v_exp_f32_e32 v80, v86
	v_exp_f32_e32 v81, v87
	v_add_f32_e32 v82, v80, v82
	v_add_f32_e32 v174, v81, v82
	v_cvt_pk_bf16_f32 v165, v80, v81
	s_waitcnt lgkmcnt(0)
	v_mfma_f32_32x32x16_bf16 v[64:79], v[166:169], v[110:113], v[64:79]
	ds_read_b128 v[80:83], v211 offset:13312
	ds_read_b128 v[84:87], v211 offset:13344
	ds_read_b128 v[182:185], v211 offset:17920
	ds_read_b128 v[222:225], v211 offset:17952
	v_exp_f32_e32 v88, v88
	v_exp_f32_e32 v89, v89
	v_add_f32_e32 v166, v88, v174
	v_add_f32_e32 v166, v89, v166
	v_cvt_pk_bf16_f32 v174, v88, v89
	v_mfma_f32_32x32x16_bf16 v[64:79], v[218:221], v[114:117], v[64:79]
	v_exp_f32_e32 v88, v90
	v_exp_f32_e32 v89, v91
	v_add_f32_e32 v90, v88, v166
	v_add_f32_e32 v90, v89, v90
	v_cvt_pk_bf16_f32 v175, v88, v89
	v_mfma_f32_32x32x16_bf16 v[64:79], v[248:251], v[118:121], v[64:79]
	v_exp_f32_e32 v88, v92
	v_exp_f32_e32 v89, v93
	v_add_f32_e32 v90, v88, v90
	v_add_f32_e32 v90, v89, v90
	v_cvt_pk_bf16_f32 v176, v88, v89
	s_waitcnt lgkmcnt(0)
	v_mfma_f32_32x32x16_bf16 v[48:63], v[80:83], v[178:181], v[48:63]
	v_exp_f32_e32 v80, v94
	v_exp_f32_e32 v81, v95
	v_add_f32_e32 v82, v80, v90
	v_add_f32_e32 v247, v81, v82
	v_cvt_pk_bf16_f32 v177, v80, v81
	v_mfma_f32_32x32x16_bf16 v[32:47], v[182:185], v[178:181], v[32:47]
	ds_read_b128 v[80:83], v199 offset:6656
	ds_read_b128 v[182:185], v199 offset:6688
	ds_read_b128 v[178:181], v199 offset:6720
	v_cmp_ge_f32_e32 vcc, s48, v247
	v_mfma_f32_32x32x16_bf16 v[48:63], v[84:87], v[170:173], v[48:63]
	v_cndmask_b32_e64 v84, 0, 1, s[6:7]
	v_cmp_ne_u32_e64 s[6:7], 0, v84
	v_mfma_f32_32x32x16_bf16 v[32:47], v[222:225], v[170:173], v[32:47]
	s_and_saveexec_b64 s[12:13], vcc
	v_cmp_gt_f32_e32 vcc, s49, v247
	s_and_b64 s[8:9], s[8:9], vcc
	s_orn2_b64 s[10:11], s[8:9], exec
	s_or_b64 exec, exec, s[12:13]
	v_cndmask_b32_e64 v84, 0, 1, s[10:11]
	v_cmp_ne_u32_e64 s[8:9], 0, v84
	v_exp_f32_e32 v64, v64
	v_exp_f32_e32 v65, v65
	s_nop 0
	v_add_f32_e32 v84, v65, v64
	v_cvt_pk_bf16_f32 v166, v64, v65
	v_exp_f32_e32 v64, v66
	ds_read_b128 v[170:173], v199 offset:6752
	ds_read_b128 v[218:221], v199 offset:6784
	ds_read_b128 v[222:225], v199 offset:6816
	v_exp_f32_e32 v65, v67
	v_add_f32_e32 v66, v64, v84
	s_waitcnt lgkmcnt(3)
	v_mfma_f32_32x32x16_bf16 v[80:95], v[80:83], v[122:125], 0
	v_add_f32_e32 v66, v65, v66
	v_cvt_pk_bf16_f32 v167, v64, v65
	v_mfma_f32_32x32x16_bf16 v[80:95], v[182:185], v[126:129], v[80:95]
	v_exp_f32_e32 v64, v68
	v_exp_f32_e32 v65, v69
	v_add_f32_e32 v66, v64, v66
	v_add_f32_e32 v66, v65, v66
	v_cvt_pk_bf16_f32 v168, v64, v65
	v_mfma_f32_32x32x16_bf16 v[80:95], v[178:181], v[130:133], v[80:95]
	v_exp_f32_e32 v64, v70
	v_exp_f32_e32 v65, v71
	v_add_f32_e32 v66, v64, v66
	v_add_f32_e32 v178, v65, v66
	v_cvt_pk_bf16_f32 v169, v64, v65
	s_waitcnt lgkmcnt(0)
	v_mfma_f32_32x32x16_bf16 v[80:95], v[170:173], v[134:137], v[80:95]
	ds_read_b128 v[64:67], v211 offset:13312
	ds_read_b128 v[68:71], v211 offset:13344
	ds_read_b128 v[182:185], v211 offset:17920
	ds_read_b128 v[248:251], v211 offset:17952
	v_exp_f32_e32 v72, v72
	v_exp_f32_e32 v73, v73
	v_add_f32_e32 v170, v72, v178
	v_add_f32_e32 v170, v73, v170
	v_cvt_pk_bf16_f32 v178, v72, v73
	v_mfma_f32_32x32x16_bf16 v[80:95], v[218:221], v[154:157], v[80:95]
	v_exp_f32_e32 v72, v74
	v_exp_f32_e32 v73, v75
	v_add_f32_e32 v74, v72, v170
	v_add_f32_e32 v74, v73, v74
	v_cvt_pk_bf16_f32 v179, v72, v73
	v_mfma_f32_32x32x16_bf16 v[80:95], v[222:225], v[158:161], v[80:95]
	v_exp_f32_e32 v72, v76
	v_exp_f32_e32 v73, v77
	v_add_f32_e32 v74, v72, v74
	v_add_f32_e32 v74, v73, v74
	v_cvt_pk_bf16_f32 v180, v72, v73
	s_waitcnt lgkmcnt(0)
	v_mfma_f32_32x32x16_bf16 v[16:31], v[64:67], v[162:165], v[16:31]
	v_exp_f32_e32 v64, v78
	v_exp_f32_e32 v65, v79
	v_add_f32_e32 v66, v64, v74
	v_add_f32_e32 v210, v65, v66
	v_cvt_pk_bf16_f32 v181, v64, v65
	v_mfma_f32_32x32x16_bf16 v[0:15], v[182:185], v[162:165], v[0:15]
	v_add_u32_e32 v226, s78, v242
	ds_read_b128 v[64:67], v226 offset:22528
	ds_read_b128 v[170:173], v226 offset:22560
	ds_read_b128 v[182:185], v226 offset:22592
	v_cmp_nge_f32_e64 s[10:11], s48, v210
	v_mfma_f32_32x32x16_bf16 v[16:31], v[68:71], v[174:177], v[16:31]
	v_exp_f32_e32 v68, v80
	v_exp_f32_e32 v69, v81
	s_nop 0
	v_add_f32_e32 v70, v69, v68
	v_cvt_pk_bf16_f32 v162, v68, v69
	v_exp_f32_e32 v80, v82
	v_exp_f32_e32 v81, v83
	v_add_f32_e32 v82, v80, v70
	v_mfma_f32_32x32x16_bf16 v[0:15], v[248:251], v[174:177], v[0:15]
	ds_read_b128 v[174:177], v226 offset:22624
	ds_read_b128 v[218:221], v226 offset:22656
	ds_read_b128 v[222:225], v226 offset:22688
	s_waitcnt lgkmcnt(3)
	v_mfma_f32_32x32x16_bf16 v[64:79], v[64:67], v[98:101], 0
	v_add_f32_e32 v82, v81, v82
	v_cvt_pk_bf16_f32 v163, v80, v81
	v_mfma_f32_32x32x16_bf16 v[64:79], v[170:173], v[102:105], v[64:79]
	v_exp_f32_e32 v80, v84
	v_exp_f32_e32 v81, v85
	v_add_f32_e32 v82, v80, v82
	v_add_f32_e32 v82, v81, v82
	v_cvt_pk_bf16_f32 v164, v80, v81
	v_mfma_f32_32x32x16_bf16 v[64:79], v[182:185], v[106:109], v[64:79]
	v_exp_f32_e32 v80, v86
	v_exp_f32_e32 v81, v87
	v_add_f32_e32 v82, v80, v82
	v_add_f32_e32 v170, v81, v82
	v_cvt_pk_bf16_f32 v165, v80, v81
	s_waitcnt lgkmcnt(0)
	v_mfma_f32_32x32x16_bf16 v[64:79], v[174:177], v[110:113], v[64:79]
	ds_read_b128 v[80:83], v211 offset:13376
	ds_read_b128 v[84:87], v211 offset:13408
	ds_read_b128 v[182:185], v211 offset:17984
	ds_read_b128 v[248:251], v211 offset:18016
	v_exp_f32_e32 v88, v88
	v_exp_f32_e32 v89, v89
	v_add_f32_e32 v170, v88, v170
	v_add_f32_e32 v171, v89, v170
	v_cvt_pk_bf16_f32 v170, v88, v89
	v_mfma_f32_32x32x16_bf16 v[64:79], v[218:221], v[114:117], v[64:79]
	v_exp_f32_e32 v88, v90
	v_exp_f32_e32 v89, v91
	v_add_f32_e32 v90, v88, v171
	v_add_f32_e32 v90, v89, v90
	v_cvt_pk_bf16_f32 v171, v88, v89
	v_mfma_f32_32x32x16_bf16 v[64:79], v[222:225], v[118:121], v[64:79]
	v_exp_f32_e32 v88, v92
	v_exp_f32_e32 v89, v93
	v_add_f32_e32 v90, v88, v90
	v_add_f32_e32 v90, v89, v90
	v_cvt_pk_bf16_f32 v172, v88, v89
	s_waitcnt lgkmcnt(0)
	v_mfma_f32_32x32x16_bf16 v[48:63], v[80:83], v[166:169], v[48:63]
	v_exp_f32_e32 v80, v94
	v_exp_f32_e32 v81, v95
	v_add_f32_e32 v82, v80, v90
	v_add_f32_e32 v211, v81, v82
	v_cvt_pk_bf16_f32 v173, v80, v81
	v_mfma_f32_32x32x16_bf16 v[32:47], v[182:185], v[166:169], v[32:47]
	ds_read_b128 v[80:83], v226 offset:22528
	ds_read_b128 v[182:185], v226 offset:22560
	ds_read_b128 v[174:177], v226 offset:22592
	v_cmp_nge_f32_e64 s[12:13], s48, v211
	v_mfma_f32_32x32x16_bf16 v[48:63], v[84:87], v[178:181], v[48:63]
	s_waitcnt lgkmcnt(0)
	s_barrier
	v_mfma_f32_32x32x16_bf16 v[32:47], v[248:251], v[178:181], v[32:47]
	s_cmpk_gt_u32 s61, 0xfc
	s_cbranch_scc1 .LBB0_933
	s_add_i32 s24, s79, 0
	v_add_u32_e32 v84, s24, v238
	v_add_u32_e32 v85, s24, v245
	v_add_u32_e32 v86, s24, v198
	s_waitcnt vmcnt(1)
	ds_write_b128 v84, v[150:153]
	s_waitcnt vmcnt(0)
	ds_write_b64 v85, v[190:191] offset:128
	ds_write_b128 v86, v[138:141] offset:13312

.LBB0_935:
	s_or_b64 s[6:7], s[8:9], s[6:7]
	v_add_f32_e32 v84, v204, v246
	v_add_f32_e32 v85, v205, v247
	s_or_b64 s[6:7], s[6:7], s[10:11]
	s_or_b64 s[6:7], s[6:7], s[12:13]
	v_pk_add_f32 v[178:179], v[84:85], v[210:211]
	s_xor_b32 s10, s77, 2
	v_add_u32_e32 v222, s78, v244
	v_exp_f32_e32 v64, v64
	v_exp_f32_e32 v65, v65
	s_nop 0
	v_add_f32_e32 v84, v65, v64
	v_cvt_pk_bf16_f32 v166, v64, v65
	v_exp_f32_e32 v64, v66
	ds_read_b128 v[204:207], v199 offset:22624
	ds_read_b128 v[208:211], v199 offset:22656
	ds_read_b128 v[218:221], v199 offset:22688
	v_exp_f32_e32 v65, v67
	v_add_f32_e32 v66, v64, v84
	s_waitcnt lgkmcnt(5)
	v_mfma_f32_32x32x16_bf16 v[80:95], v[80:83], v[122:125], 0
	v_add_f32_e32 v66, v65, v66
	v_cvt_pk_bf16_f32 v167, v64, v65
	s_waitcnt lgkmcnt(3)
	v_mfma_f32_32x32x16_bf16 v[80:95], v[182:185], v[126:129], v[80:95]
	v_exp_f32_e32 v64, v68
	v_exp_f32_e32 v65, v69
	v_add_f32_e32 v66, v64, v66
	v_add_f32_e32 v66, v65, v66
	v_cvt_pk_bf16_f32 v168, v64, v65
	v_mfma_f32_32x32x16_bf16 v[80:95], v[174:177], v[130:133], v[80:95]
	v_exp_f32_e32 v64, v70
	v_exp_f32_e32 v65, v71
	v_add_f32_e32 v66, v64, v66
	v_add_f32_e32 v174, v65, v66
	v_cvt_pk_bf16_f32 v169, v64, v65
	s_waitcnt lgkmcnt(0)
	v_mfma_f32_32x32x16_bf16 v[80:95], v[204:207], v[134:137], v[80:95]
	ds_read_b128 v[64:67], v222 offset:13376
	ds_read_b128 v[68:71], v222 offset:13408
	ds_read_b128 v[180:183], v222 offset:17984
	ds_read_b128 v[222:225], v222 offset:18016
	v_exp_f32_e32 v72, v72
	v_exp_f32_e32 v73, v73
	v_add_f32_e32 v174, v72, v174
	v_add_f32_e32 v175, v73, v174
	v_cvt_pk_bf16_f32 v174, v72, v73
	v_mfma_f32_32x32x16_bf16 v[80:95], v[208:211], v[154:157], v[80:95]
	v_exp_f32_e32 v72, v74
	v_exp_f32_e32 v73, v75
	v_add_f32_e32 v74, v72, v175
	v_add_f32_e32 v74, v73, v74
	v_cvt_pk_bf16_f32 v175, v72, v73
	v_mfma_f32_32x32x16_bf16 v[80:95], v[218:221], v[158:161], v[80:95]
	v_exp_f32_e32 v72, v76
	v_exp_f32_e32 v73, v77
	v_add_f32_e32 v74, v72, v74
	v_add_f32_e32 v74, v73, v74
	v_cvt_pk_bf16_f32 v176, v72, v73
	s_waitcnt lgkmcnt(0)
	v_mfma_f32_32x32x16_bf16 v[16:31], v[64:67], v[162:165], v[16:31]
	v_exp_f32_e32 v64, v78
	v_exp_f32_e32 v65, v79
	v_add_f32_e32 v66, v64, v74
	v_add_f32_e32 v204, v65, v66
	v_cvt_pk_bf16_f32 v177, v64, v65
	v_mfma_f32_32x32x16_bf16 v[0:15], v[180:183], v[162:165], v[0:15]
	ds_read_b128 v[64:67], v199 offset:29184
	ds_read_b128 v[180:183], v199 offset:29216
	ds_read_b128 v[208:211], v199 offset:29248
	v_cmp_nge_f32_e32 vcc, s48, v204
	v_mfma_f32_32x32x16_bf16 v[16:31], v[68:71], v[170:173], v[16:31]
	v_mfma_f32_32x32x16_bf16 v[0:15], v[222:225], v[170:173], v[0:15]
	v_mad_u32_u24 v68, v187, s69, v186
	v_add_u32_e32 v206, s76, v68
	v_exp_f32_e32 v68, v80
	v_exp_f32_e32 v69, v81
	s_nop 0
	v_add_f32_e32 v70, v69, v68
	v_cvt_pk_bf16_f32 v162, v68, v69
	v_exp_f32_e32 v80, v82
	ds_read_b128 v[170:173], v199 offset:29280
	ds_read_b128 v[218:221], v199 offset:29312
	ds_read_b128 v[222:225], v199 offset:29344
	v_exp_f32_e32 v81, v83
	v_add_f32_e32 v82, v80, v70
	s_waitcnt lgkmcnt(3)
	v_mfma_f32_32x32x16_bf16 v[64:79], v[64:67], v[98:101], 0
	v_add_f32_e32 v82, v81, v82
	v_cvt_pk_bf16_f32 v163, v80, v81
	v_mfma_f32_32x32x16_bf16 v[64:79], v[180:183], v[102:105], v[64:79]
	v_exp_f32_e32 v80, v84
	v_exp_f32_e32 v81, v85
	v_add_f32_e32 v82, v80, v82
	v_add_f32_e32 v82, v81, v82
	v_cvt_pk_bf16_f32 v164, v80, v81
	v_mfma_f32_32x32x16_bf16 v[64:79], v[208:211], v[106:109], v[64:79]
	v_exp_f32_e32 v80, v86
	v_exp_f32_e32 v81, v87
	v_add_f32_e32 v82, v80, v82
	v_add_f32_e32 v184, v81, v82
	v_cvt_pk_bf16_f32 v165, v80, v81
	s_waitcnt lgkmcnt(0)
	v_mfma_f32_32x32x16_bf16 v[64:79], v[170:173], v[110:113], v[64:79]
	ds_read_b128 v[80:83], v206 offset:35840
	ds_read_b128 v[84:87], v206 offset:35872
	ds_read_b128 v[180:183], v206 offset:40448
	ds_read_b128 v[208:211], v206 offset:40480
	v_exp_f32_e32 v88, v88
	v_exp_f32_e32 v89, v89
	v_add_f32_e32 v170, v88, v184
	v_add_f32_e32 v171, v89, v170
	v_cvt_pk_bf16_f32 v170, v88, v89
	v_mfma_f32_32x32x16_bf16 v[64:79], v[218:221], v[114:117], v[64:79]
	v_exp_f32_e32 v88, v90
	v_exp_f32_e32 v89, v91
	v_add_f32_e32 v90, v88, v171
	v_add_f32_e32 v90, v89, v90
	v_cvt_pk_bf16_f32 v171, v88, v89
	v_mfma_f32_32x32x16_bf16 v[64:79], v[222:225], v[118:121], v[64:79]
	v_exp_f32_e32 v88, v92
	v_exp_f32_e32 v89, v93
	v_add_f32_e32 v90, v88, v90
	v_add_f32_e32 v90, v89, v90
	v_cvt_pk_bf16_f32 v172, v88, v89
	s_waitcnt lgkmcnt(0)
	v_mfma_f32_32x32x16_bf16 v[48:63], v[80:83], v[166:169], v[48:63]
	v_exp_f32_e32 v80, v94
	v_exp_f32_e32 v81, v95
	v_add_f32_e32 v82, v80, v90
	v_add_f32_e32 v205, v81, v82
	v_cvt_pk_bf16_f32 v173, v80, v81
	v_mfma_f32_32x32x16_bf16 v[32:47], v[180:183], v[166:169], v[32:47]
	ds_read_b128 v[80:83], v199 offset:29184
	ds_read_b128 v[166:169], v199 offset:29216
	ds_read_b128 v[182:185], v199 offset:29248
	s_or_b64 s[8:9], s[6:7], vcc
	v_cmp_nge_f32_e32 vcc, s48, v205
	v_pk_add_f32 v[204:205], v[178:179], v[204:205]
	v_mfma_f32_32x32x16_bf16 v[48:63], v[84:87], v[174:177], v[48:63]
	v_exp_f32_e32 v64, v64
	v_exp_f32_e32 v65, v65
	s_nop 0
	v_add_f32_e32 v84, v65, v64
	v_cvt_pk_bf16_f32 v178, v64, v65
	v_exp_f32_e32 v64, v66
	v_exp_f32_e32 v65, v67
	v_add_f32_e32 v66, v64, v84
	v_mfma_f32_32x32x16_bf16 v[32:47], v[208:211], v[174:177], v[32:47]
	ds_read_b128 v[174:177], v199 offset:29280
	ds_read_b128 v[208:211], v199 offset:29312
	ds_read_b128 v[218:221], v199 offset:29344
	s_waitcnt lgkmcnt(3)
	v_mfma_f32_32x32x16_bf16 v[80:95], v[80:83], v[122:125], 0
	v_add_f32_e32 v66, v65, v66
	v_cvt_pk_bf16_f32 v179, v64, v65
	v_mfma_f32_32x32x16_bf16 v[80:95], v[166:169], v[126:129], v[80:95]
	v_exp_f32_e32 v64, v68
	v_exp_f32_e32 v65, v69
	v_add_f32_e32 v66, v64, v66
	v_add_f32_e32 v66, v65, v66
	v_cvt_pk_bf16_f32 v180, v64, v65
	v_mfma_f32_32x32x16_bf16 v[80:95], v[182:185], v[130:133], v[80:95]
	v_exp_f32_e32 v64, v70
	v_exp_f32_e32 v65, v71
	v_add_f32_e32 v66, v64, v66
	v_add_f32_e32 v182, v65, v66
	v_cvt_pk_bf16_f32 v181, v64, v65
	s_waitcnt lgkmcnt(0)
	v_mfma_f32_32x32x16_bf16 v[80:95], v[174:177], v[134:137], v[80:95]
	ds_read_b128 v[64:67], v206 offset:35840
	ds_read_b128 v[68:71], v206 offset:35872
	ds_read_b128 v[166:169], v206 offset:40448
	ds_read_b128 v[222:225], v206 offset:40480
	v_exp_f32_e32 v72, v72
	v_exp_f32_e32 v73, v73
	v_add_f32_e32 v174, v72, v182
	v_add_f32_e32 v174, v73, v174
	v_cvt_pk_bf16_f32 v182, v72, v73
	v_mfma_f32_32x32x16_bf16 v[80:95], v[208:211], v[154:157], v[80:95]
	v_exp_f32_e32 v72, v74
	v_exp_f32_e32 v73, v75
	v_add_f32_e32 v74, v72, v174
	v_add_f32_e32 v74, v73, v74
	v_cvt_pk_bf16_f32 v183, v72, v73
	v_mfma_f32_32x32x16_bf16 v[80:95], v[218:221], v[158:161], v[80:95]
	v_exp_f32_e32 v72, v76
	v_exp_f32_e32 v73, v77
	v_add_f32_e32 v74, v72, v74
	v_add_f32_e32 v74, v73, v74
	v_cvt_pk_bf16_f32 v184, v72, v73
	s_waitcnt lgkmcnt(0)
	v_mfma_f32_32x32x16_bf16 v[16:31], v[64:67], v[162:165], v[16:31]
	v_exp_f32_e32 v64, v78
	v_exp_f32_e32 v65, v79
	v_add_f32_e32 v66, v64, v74
	v_add_f32_e32 v226, v65, v66
	v_cvt_pk_bf16_f32 v185, v64, v65
	v_mfma_f32_32x32x16_bf16 v[0:15], v[166:169], v[162:165], v[0:15]
	s_mulk_i32 s10, 0x5800
	v_add_u32_e32 v199, s10, v242
	ds_read_b128 v[64:67], v199
	ds_read_b128 v[164:167], v199 offset:32
	ds_read_b128 v[174:177], v199 offset:64
	v_cmp_nge_f32_e64 s[6:7], s48, v226
	v_mfma_f32_32x32x16_bf16 v[16:31], v[68:71], v[170:173], v[16:31]
	v_exp_f32_e32 v68, v80
	v_exp_f32_e32 v69, v81
	s_nop 0
	v_add_f32_e32 v70, v69, v68
	v_cvt_pk_bf16_f32 v162, v68, v69
	v_exp_f32_e32 v80, v82
	v_exp_f32_e32 v81, v83
	v_add_f32_e32 v82, v80, v70
	v_mfma_f32_32x32x16_bf16 v[0:15], v[222:225], v[170:173], v[0:15]
	s_or_b64 s[8:9], s[8:9], vcc
	ds_read_b128 v[168:171], v199 offset:96
	ds_read_b128 v[208:211], v199 offset:128
	ds_read_b128 v[218:221], v199 offset:160
	s_waitcnt lgkmcnt(3)
	v_mfma_f32_32x32x16_bf16 v[64:79], v[64:67], v[98:101], 0
	v_add_f32_e32 v82, v81, v82
	v_cvt_pk_bf16_f32 v163, v80, v81
	v_mfma_f32_32x32x16_bf16 v[64:79], v[164:167], v[102:105], v[64:79]
	v_exp_f32_e32 v80, v84
	v_exp_f32_e32 v81, v85
	v_add_f32_e32 v82, v80, v82
	v_add_f32_e32 v82, v81, v82
	v_cvt_pk_bf16_f32 v164, v80, v81
	v_mfma_f32_32x32x16_bf16 v[64:79], v[174:177], v[106:109], v[64:79]
	v_exp_f32_e32 v80, v86
	v_exp_f32_e32 v81, v87
	v_add_f32_e32 v82, v80, v82
	v_add_f32_e32 v166, v81, v82
	v_cvt_pk_bf16_f32 v165, v80, v81
	s_waitcnt lgkmcnt(0)
	v_mfma_f32_32x32x16_bf16 v[64:79], v[168:171], v[110:113], v[64:79]
	ds_read_b128 v[80:83], v206 offset:35904
	ds_read_b128 v[84:87], v206 offset:35936
	ds_read_b128 v[222:225], v206 offset:40512
	ds_read_b128 v[246:249], v206 offset:40544
	v_exp_f32_e32 v88, v88
	v_exp_f32_e32 v89, v89
	v_add_f32_e32 v166, v88, v166
	v_add_f32_e32 v167, v89, v166
	v_cvt_pk_bf16_f32 v166, v88, v89
	v_mfma_f32_32x32x16_bf16 v[64:79], v[208:211], v[114:117], v[64:79]
	v_exp_f32_e32 v88, v90
	v_exp_f32_e32 v89, v91
	v_add_f32_e32 v90, v88, v167
	v_add_f32_e32 v90, v89, v90
	v_cvt_pk_bf16_f32 v167, v88, v89
	v_mfma_f32_32x32x16_bf16 v[64:79], v[218:221], v[118:121], v[64:79]
	v_exp_f32_e32 v88, v92
	v_exp_f32_e32 v89, v93
	v_add_f32_e32 v90, v88, v90
	v_add_f32_e32 v90, v89, v90
	v_cvt_pk_bf16_f32 v168, v88, v89
	s_waitcnt lgkmcnt(0)
	v_mfma_f32_32x32x16_bf16 v[48:63], v[80:83], v[178:181], v[48:63]
	v_exp_f32_e32 v80, v94
	v_exp_f32_e32 v81, v95
	v_add_f32_e32 v82, v80, v90
	v_add_f32_e32 v227, v81, v82
	v_cvt_pk_bf16_f32 v169, v80, v81
	v_mfma_f32_32x32x16_bf16 v[32:47], v[222:225], v[178:181], v[32:47]
	ds_read_b128 v[80:83], v199
	ds_read_b128 v[174:177], v199 offset:32
	ds_read_b128 v[170:173], v199 offset:64
	s_or_b64 s[6:7], s[8:9], s[6:7]
	v_cmp_nge_f32_e32 vcc, s48, v227
	s_or_b64 s[6:7], s[6:7], vcc
	s_cmp_lg_u64 s[6:7], 0
	s_cselect_b64 s[6:7], -1, 0
	s_or_b64 s[42:43], s[42:43], s[6:7]
	v_mfma_f32_32x32x16_bf16 v[48:63], v[84:87], v[182:185], v[48:63]
	v_add_f32_e64 v204, v204, v226
	v_add_f32_e64 v205, v205, v227
	s_waitcnt lgkmcnt(0)
	s_barrier
	v_mfma_f32_32x32x16_bf16 v[32:47], v[246:249], v[182:185], v[32:47]
	s_add_u32 s40, s40, 0x40000
	s_mov_b64 s[6:7], 0x2000
	s_addc_u32 s41, s41, 0
	v_lshl_add_u64 v[202:203], v[202:203], 0, s[6:7]
	s_and_b64 vcc, exec, s[44:45]
	s_cbranch_vccnz .LBB0_937
	s_mov_b32 s61, s30
	s_branch .LBB0_923
